# stack25 + ctx LayerNorm folded under the N=1024 GEMM phases: grid barrier replaced by a split-K slice counter, slice owners skip the LayerNorm, other workgroups do two rows per wave
# speedup vs baseline: 1.0308x; 1.0221x over previous
.LBB0_327:
	s_and_b64 vcc, exec, s[6:7]
	s_movk_i32 s87, 0xff7d
	s_cbranch_vccnz .LBB0_331
	s_lshr_b32 s6, s97, 5
	s_and_b32 s6, s6, 0x7800000
	v_lshl_or_b32 v156, s22, 8, v154
	s_add_u32 s22, s83, s6
	s_addc_u32 s33, s95, 0
	s_lshl_b32 s6, s82, 8
	s_ashr_i32 s7, s6, 31
	s_lshl_b64 s[6:7], s[6:7], 12
	s_add_u32 s6, s22, s6
	s_addc_u32 s7, s33, s7
	v_ashrrev_i32_e32 v157, 31, v156
	v_lshl_add_u64 v[156:157], v[156:157], 2, s[6:7]
	s_brev_b32 s6, 63
	s_mov_b32 s7, -1
	v_lshl_add_u64 v[156:157], v[156:157], 0, s[6:7]
	v_lshl_add_u64 v[158:159], v[156:157], 0, v[132:133]
	global_store_dwordx4 v[158:159], v[126:129], off sc0 sc1
	global_store_dwordx4 v[158:159], v[106:109], off offset:64 sc0 sc1
	global_store_dwordx4 v[158:159], v[66:69], off offset:512 sc0 sc1
	global_store_dwordx4 v[158:159], v[86:89], off offset:576 sc0 sc1
	s_andn2_b64 vcc, exec, s[26:27]
	v_lshl_add_u64 v[66:67], v[156:157], 0, v[134:135]
	global_store_dwordx4 v[66:67], v[122:125], off sc0 sc1
	global_store_dwordx4 v[66:67], v[98:101], off offset:64 sc0 sc1
	global_store_dwordx4 v[66:67], v[54:57], off offset:512 sc0 sc1
	global_store_dwordx4 v[66:67], v[82:85], off offset:576 sc0 sc1
	s_nop 0
	v_lshl_add_u64 v[54:55], v[156:157], 0, v[136:137]
	global_store_dwordx4 v[54:55], v[118:121], off sc0 sc1
	global_store_dwordx4 v[54:55], v[90:93], off offset:64 sc0 sc1
	global_store_dwordx4 v[54:55], v[46:49], off offset:512 sc0 sc1
	global_store_dwordx4 v[54:55], v[26:29], off offset:576 sc0 sc1
	s_nop 1
	v_lshl_add_u64 v[26:27], v[156:157], 0, v[138:139]
	global_store_dwordx4 v[26:27], v[114:117], off sc0 sc1
	global_store_dwordx4 v[26:27], v[78:81], off offset:64 sc0 sc1
	global_store_dwordx4 v[26:27], v[42:45], off offset:512 sc0 sc1
	global_store_dwordx4 v[26:27], v[18:21], off offset:576 sc0 sc1
	s_nop 1
	v_lshl_add_u64 v[18:19], v[156:157], 0, v[140:141]
	global_store_dwordx4 v[18:19], v[110:113], off sc0 sc1
	global_store_dwordx4 v[18:19], v[70:73], off offset:64 sc0 sc1
	global_store_dwordx4 v[18:19], v[38:41], off offset:512 sc0 sc1
	global_store_dwordx4 v[18:19], v[14:17], off offset:576 sc0 sc1
	s_nop 1
	v_lshl_add_u64 v[14:15], v[156:157], 0, v[142:143]
	global_store_dwordx4 v[14:15], v[102:105], off sc0 sc1
	global_store_dwordx4 v[14:15], v[62:65], off offset:64 sc0 sc1
	global_store_dwordx4 v[14:15], v[34:37], off offset:512 sc0 sc1
	global_store_dwordx4 v[14:15], v[10:13], off offset:576 sc0 sc1
	s_nop 1
	v_lshl_add_u64 v[10:11], v[156:157], 0, v[144:145]
	global_store_dwordx4 v[10:11], v[94:97], off sc0 sc1
	global_store_dwordx4 v[10:11], v[58:61], off offset:64 sc0 sc1
	global_store_dwordx4 v[10:11], v[30:33], off offset:512 sc0 sc1
	global_store_dwordx4 v[10:11], v[6:9], off offset:576 sc0 sc1
	s_nop 1
	v_lshl_add_u64 v[6:7], v[156:157], 0, v[146:147]
	global_store_dwordx4 v[6:7], v[74:77], off sc0 sc1
	global_store_dwordx4 v[6:7], v[50:53], off offset:64 sc0 sc1
	global_store_dwordx4 v[6:7], v[22:25], off offset:512 sc0 sc1
	global_store_dwordx4 v[6:7], v[2:5], off offset:576 sc0 sc1
	s_waitcnt vmcnt(0)
	s_barrier
	v_readlane_b32 s98, v253, 0
	s_cmp_lg_u32 s98, 0
	s_cbranch_scc1 .Lmy_sig_skip_dn
	v_readlane_b32 s98, v254, 56
	v_readlane_b32 s99, v254, 57
	s_nop 3
	s_load_dwordx2 s[98:99], s[98:99], 0x88
	v_readlane_b32 s100, v254, 54
	s_lshl_b32 s100, s100, 8
	s_add_i32 s100, s100, 0x40000
	s_waitcnt lgkmcnt(0)
	s_add_u32 s98, s98, s100
	s_addc_u32 s99, s99, 0
	s_mov_b64 s[100:101], exec
	s_mov_b64 exec, 1
	global_atomic_add v1, v245, s[98:99]
	s_mov_b64 exec, s[100:101]
.Lmy_sig_skip_dn:
	s_cbranch_vccnz .LBB0_330
	s_barrier

.LBB0_516:
	s_waitcnt vmcnt(0)
	s_waitcnt lgkmcnt(0)
	s_barrier
	s_and_saveexec_b64 s[4:5], s[8:9]
	s_cbranch_execz .LBB0_631
	v_readlane_b32 s98, v254, 63
	s_and_b32 s98, s98, 32
	s_cmp_eq_u32 s98, 0
	s_cbranch_scc1 .LBB0_631
	v_readlane_b32 s98, v254, 54
	s_lshl_b32 s98, s98, 8
	s_add_i32 s98, s98, 0x40000
	s_add_u32 s98, s6, s98
	s_addc_u32 s99, s7, 0
	s_mov_b32 s100, 0
.Lmy_c1_poll:
	global_load_dword v0, v1, s[98:99] sc1
	s_waitcnt vmcnt(0)
	v_readfirstlane_b32 s101, v0
	s_nop 3
	s_cmp_ge_u32 s101, 0x80
	s_cbranch_scc1 .Lmy_c1_done
	s_sleep 1
	s_add_i32 s100, s100, 1
	s_cmp_lt_u32 s100, 0x4000
	s_cbranch_scc1 .Lmy_c1_poll
.Lmy_c1_done:
	buffer_inv sc1
	s_waitcnt vmcnt(0)
	s_branch .LBB0_631
	v_readlane_b32 s2, v254, 43
	s_waitcnt vmcnt(0) expcnt(0) lgkmcnt(0)
	s_nop 0
	v_mov_b32_e32 v0, s2
	ds_read_b32 v3, v0
	v_readlane_b32 s2, v254, 44
	s_waitcnt lgkmcnt(0)
	v_cmp_ne_u32_e32 vcc, 0, v3
	v_mov_b32_e32 v0, s2
	ds_read_b32 v2, v0
	s_cbranch_vccnz .LBB0_595
	s_add_u32 s8, s6, 0x80200
	s_addc_u32 s9, s7, 0
	s_add_u32 s10, s6, 0x80400
	s_addc_u32 s11, s7, 0
	s_add_u32 s14, s6, 0x80500
	s_addc_u32 s15, s7, 0
	s_add_u32 s18, s6, 0x80600
	s_addc_u32 s19, s7, 0
	s_add_u32 s20, s6, 0x80700
	s_addc_u32 s21, s7, 0
	s_add_u32 s22, s6, 0x80800
	s_addc_u32 s23, s7, 0
	s_add_u32 s24, s6, 0x80900
	s_addc_u32 s25, s7, 0
	s_add_u32 s26, s6, 0x80a00
	s_addc_u32 s27, s7, 0
	s_add_u32 s28, s6, 0x80b00
	s_addc_u32 s29, s7, 0
	s_add_u32 s30, s6, 0x80c00
	s_addc_u32 s31, s7, 0
	s_add_u32 s34, s6, 0x80d00
	s_addc_u32 s35, s7, 0
	s_add_u32 s36, s6, 0x80e00
	s_addc_u32 s37, s7, 0
	s_add_u32 s38, s6, 0x80f00
	s_addc_u32 s39, s7, 0
	s_add_u32 s62, s6, 0x81000
	s_addc_u32 s63, s7, 0
	s_add_u32 s64, s6, 0x81100
	s_addc_u32 s65, s7, 0
	s_add_u32 s80, s6, 0x81200
	s_addc_u32 s81, s7, 0
	s_add_u32 s84, s6, 0x81300
	s_addc_u32 s85, s7, 0
	s_mov_b32 s2, 1
	s_branch .LBB0_521

.LBB0_631:
	s_or_b64 exec, exec, s[4:5]
	v_readlane_b32 s4, v254, 11
	v_readlane_b32 s5, v254, 12
	s_mov_b64 s[6:7], s[70:71]
	s_andn2_b64 vcc, exec, s[4:5]
	s_waitcnt lgkmcnt(0)
	v_cndmask_b32_e64 v2, 0, 1, s[4:5]
	v_cmp_ne_u32_e64 s[8:9], 1, v2
	s_barrier
	s_nop 0
	v_writelane_b32 v253, s8, 3
	v_mbcnt_lo_u32_b32 v0, -1, 0
	v_mbcnt_hi_u32_b32 v0, -1, v0
	s_nop 1
	v_writelane_b32 v253, s9, 4
	s_cbranch_vccnz .LBB0_642
	v_readlane_b32 s98, v254, 63
	s_and_b32 s98, s98, 32
	s_cmp_eq_u32 s98, 0
	s_cbranch_scc1 .LBB0_642
	s_mov_b32 s99, 0
.Lmy_ln1_again:
	s_mov_b64 s[6:7], s[70:71]
	v_mbcnt_lo_u32_b32 v0, -1, 0
	v_mbcnt_hi_u32_b32 v0, -1, v0
	s_load_dwordx2 s[10:11], s[6:7], 0x88
	s_load_dwordx4 s[12:15], s[6:7], 0x30
	v_readlane_b32 s4, v253, 9
	v_readlane_b32 s5, v253, 10
	s_lshl_b64 s[4:5], s[4:5], 2
	s_waitcnt lgkmcnt(0)
	s_add_u32 s2, s10, s4
	s_addc_u32 s4, s11, s5
	s_add_u32 s2, s2, 0x100000
	v_lshlrev_b32_e32 v2, 2, v0
	v_and_b32_e32 v0, 64, v249
	s_addc_u32 s16, s4, 0
	s_lshl_b32 s4, s42, 2
	v_add_u32_e32 v3, 64, v0
	v_xor_b32_e32 v0, 1, v249
	s_add_u32 s4, s2, s4
	v_cmp_lt_i32_e32 vcc, v0, v3
	v_xor_b32_e32 v4, 2, v249
	s_addc_u32 s5, s16, 0
	s_lshl_b64 s[6:7], s[66:67], 2
	v_cndmask_b32_e32 v0, v249, v0, vcc
	v_cmp_lt_i32_e32 vcc, v4, v3
	s_add_u32 s8, s14, s6
	s_addc_u32 s9, s15, s7
	v_cndmask_b32_e32 v4, v249, v4, vcc
	v_lshlrev_b32_e32 v50, 2, v4
	v_xor_b32_e32 v4, 4, v249
	s_add_u32 s6, s12, s6
	v_cmp_lt_i32_e32 vcc, v4, v3
	s_addc_u32 s7, s13, s7
	s_add_u32 s14, s10, 0x151000
	v_cndmask_b32_e32 v4, v249, v4, vcc
	v_readlane_b32 s12, v253, 5
	v_lshlrev_b32_e32 v51, 2, v4
	v_xor_b32_e32 v4, 8, v249
	s_addc_u32 s15, s11, 0
	v_readlane_b32 s13, v253, 6
	v_cmp_lt_i32_e32 vcc, v4, v3
	s_and_b64 s[12:13], s[12:13], exec
	v_readlane_b32 s12, v253, 13
	v_cndmask_b32_e32 v4, v249, v4, vcc
	v_lshlrev_b32_e32 v52, 2, v4
	v_xor_b32_e32 v4, 16, v249
	v_readlane_b32 s13, v253, 14
	v_cmp_lt_i32_e32 vcc, v4, v3
	s_cselect_b32 s14, s14, 0
	s_cselect_b32 s15, s15, 0
	s_and_b64 s[12:13], s[12:13], exec
	v_cndmask_b32_e32 v4, v249, v4, vcc
	s_cselect_b32 s13, s16, s15
	s_cselect_b32 s12, s2, s14
	v_lshlrev_b32_e32 v53, 2, v4
	v_xor_b32_e32 v4, 32, v249
	v_cmp_lt_i32_e32 vcc, v4, v3
	s_cmp_lg_u64 s[12:13], 0
	s_cselect_b64 s[14:15], -1, 0
	v_cndmask_b32_e32 v3, v249, v4, vcc
	s_lshl_b32 s2, s33, 2
	v_lshlrev_b32_e32 v54, 2, v3
	s_add_u32 s12, s12, s2
	v_ashrrev_i32_e32 v3, 31, v2
	s_addc_u32 s13, s13, 0
	v_lshlrev_b64 v[4:5], 2, v[2:3]
	v_lshl_add_u64 v[6:7], s[4:5], 0, v[4:5]
	v_lshl_add_u64 v[14:15], s[12:13], 0, v[4:5]
	s_mov_b64 s[4:5], 0x49000
	v_lshl_add_u64 v[12:13], v[14:15], 0, s[4:5]
	v_readlane_b32 s4, v254, 48
	v_lshlrev_b64 v[2:3], 1, v[2:3]
	v_readlane_b32 s5, v254, 49
	s_mov_b64 s[16:17], 0x48000
	v_lshlrev_b32_e32 v0, 2, v0
	v_lshl_add_u64 v[16:17], s[4:5], 0, v[2:3]
	v_readlane_b32 s4, v254, 35
	v_readlane_b32 s5, v254, 36
	v_lshl_add_u64 v[6:7], v[6:7], 0, s[16:17]
	v_lshl_add_u64 v[8:9], s[6:7], 0, v[4:5]
	v_lshl_add_u64 v[18:19], s[4:5], 0, v[2:3]
	v_readlane_b32 s4, v254, 37
	v_readlane_b32 s5, v254, 38
	v_lshl_add_u64 v[10:11], s[8:9], 0, v[4:5]
	v_lshl_add_u64 v[14:15], v[14:15], 0, s[16:17]
	v_lshl_add_u64 v[20:21], s[4:5], 0, v[4:5]
	v_readlane_b32 s4, v254, 46
	v_readlane_b32 s5, v254, 47
	s_mov_b32 s2, 0x5200000
	s_mov_b32 s5, 0x9a00000
	s_cmp_eq_u32 s99, 0
	s_cbranch_scc1 .Lmy_ln1_nd
	s_add_i32 s4, s4, 0xffffff00
	s_mov_b32 s100, 0xfff80000
	s_mov_b32 s101, -1
	v_lshl_add_u64 v[16:17], v[16:17], 0, s[100:101]
	v_lshl_add_u64 v[18:19], v[18:19], 0, s[100:101]
	s_mov_b32 s100, 0xfff00000
	v_lshl_add_u64 v[20:21], v[20:21], 0, s[100:101]
.Lmy_ln1_nd:
	s_branch .LBB0_634
.LBB0_633:
	v_readlane_b32 s6, v254, 50
	v_readlane_b32 s7, v254, 51
	s_add_i32 s4, s4, s38
	s_cmpk_lt_i32 s4, 0x4800
	v_lshl_add_u64 v[16:17], v[16:17], 0, s[6:7]
	v_lshl_add_u64 v[18:19], v[18:19], 0, s[6:7]
	v_readlane_b32 s6, v254, 52
	v_readlane_b32 s7, v254, 53
	s_nop 1
	v_lshl_add_u64 v[20:21], v[20:21], 0, s[6:7]
	s_cbranch_scc0 .Lmy_ln1_end

.Lmy_ln1_end:
	s_xor_b32 s99, s99, 1
	s_cmp_lg_u32 s99, 0
	s_cbranch_scc1 .Lmy_ln1_again

.LBB0_1167:
	s_and_b64 vcc, exec, s[6:7]
	s_movk_i32 s65, 0xff5d
	s_movk_i32 s64, 0xff7c
	s_cbranch_vccnz .LBB0_1171
	s_lshr_b32 s2, s86, 5
	s_and_b32 s2, s2, 0x7800000
	s_add_u32 s2, s15, s2
	v_lshl_or_b32 v156, s16, 8, v154
	s_addc_u32 s16, s52, 0
	s_lshl_b32 s6, s14, 8
	s_ashr_i32 s7, s6, 31
	s_lshl_b64 s[6:7], s[6:7], 12
	s_add_u32 s6, s2, s6
	s_addc_u32 s7, s16, s7
	v_ashrrev_i32_e32 v157, 31, v156
	v_lshl_add_u64 v[156:157], v[156:157], 2, s[6:7]
	s_brev_b32 s6, 63
	s_mov_b32 s7, -1
	v_lshl_add_u64 v[156:157], v[156:157], 0, s[6:7]
	v_lshl_add_u64 v[158:159], v[156:157], 0, v[132:133]
	global_store_dwordx4 v[158:159], v[122:125], off sc0 sc1
	global_store_dwordx4 v[158:159], v[102:105], off offset:64 sc0 sc1
	global_store_dwordx4 v[158:159], v[70:73], off offset:512 sc0 sc1
	global_store_dwordx4 v[158:159], v[126:129], off offset:576 sc0 sc1
	s_andn2_b64 vcc, exec, s[20:21]
	v_lshl_add_u64 v[70:71], v[156:157], 0, v[134:135]
	global_store_dwordx4 v[70:71], v[118:121], off sc0 sc1
	global_store_dwordx4 v[70:71], v[94:97], off offset:64 sc0 sc1
	global_store_dwordx4 v[70:71], v[66:69], off offset:512 sc0 sc1
	global_store_dwordx4 v[70:71], v[42:45], off offset:576 sc0 sc1
	s_nop 1
	v_lshl_add_u64 v[42:43], v[156:157], 0, v[136:137]
	global_store_dwordx4 v[42:43], v[114:117], off sc0 sc1
	global_store_dwordx4 v[42:43], v[90:93], off offset:64 sc0 sc1
	global_store_dwordx4 v[42:43], v[50:53], off offset:512 sc0 sc1
	global_store_dwordx4 v[42:43], v[30:33], off offset:576 sc0 sc1
	s_nop 1
	v_lshl_add_u64 v[30:31], v[156:157], 0, v[138:139]
	global_store_dwordx4 v[30:31], v[110:113], off sc0 sc1
	global_store_dwordx4 v[30:31], v[82:85], off offset:64 sc0 sc1
	global_store_dwordx4 v[30:31], v[46:49], off offset:512 sc0 sc1
	global_store_dwordx4 v[30:31], v[26:29], off offset:576 sc0 sc1
	s_nop 1
	v_lshl_add_u64 v[26:27], v[156:157], 0, v[140:141]
	global_store_dwordx4 v[26:27], v[106:109], off sc0 sc1
	global_store_dwordx4 v[26:27], v[74:77], off offset:64 sc0 sc1
	global_store_dwordx4 v[26:27], v[38:41], off offset:512 sc0 sc1
	global_store_dwordx4 v[26:27], v[22:25], off offset:576 sc0 sc1
	s_nop 1
	v_lshl_add_u64 v[22:23], v[156:157], 0, v[142:143]
	global_store_dwordx4 v[22:23], v[98:101], off sc0 sc1
	global_store_dwordx4 v[22:23], v[62:65], off offset:64 sc0 sc1
	global_store_dwordx4 v[22:23], v[34:37], off offset:512 sc0 sc1
	global_store_dwordx4 v[22:23], v[14:17], off offset:576 sc0 sc1
	s_nop 1
	v_lshl_add_u64 v[14:15], v[156:157], 0, v[144:145]
	global_store_dwordx4 v[14:15], v[86:89], off sc0 sc1
	global_store_dwordx4 v[14:15], v[58:61], off offset:64 sc0 sc1
	global_store_dwordx4 v[14:15], v[18:21], off offset:512 sc0 sc1
	global_store_dwordx4 v[14:15], v[6:9], off offset:576 sc0 sc1
	s_nop 1
	v_lshl_add_u64 v[6:7], v[156:157], 0, v[146:147]
	global_store_dwordx4 v[6:7], v[78:81], off sc0 sc1
	global_store_dwordx4 v[6:7], v[54:57], off offset:64 sc0 sc1
	global_store_dwordx4 v[6:7], v[10:13], off offset:512 sc0 sc1
	global_store_dwordx4 v[6:7], v[2:5], off offset:576 sc0 sc1
	s_waitcnt vmcnt(0)
	s_barrier
	v_readlane_b32 s98, v253, 0
	s_cmp_lg_u32 s98, 0
	s_cbranch_scc1 .Lmy_sig_skip_op
	v_readlane_b32 s98, v254, 56
	v_readlane_b32 s99, v254, 57
	s_nop 3
	s_load_dwordx2 s[98:99], s[98:99], 0x88
	s_movk_i32 s100, 4
	s_lshl_b32 s100, s100, 8
	s_add_i32 s100, s100, 0x40000
	s_waitcnt lgkmcnt(0)
	s_add_u32 s98, s98, s100
	s_addc_u32 s99, s99, 0
	s_mov_b64 s[100:101], exec
	s_mov_b64 exec, 1
	global_atomic_add v1, v245, s[98:99]
	s_mov_b64 exec, s[100:101]

.LBB0_1216:
	s_waitcnt vmcnt(0)
	s_waitcnt lgkmcnt(0)
	s_barrier
	s_and_saveexec_b64 s[6:7], s[10:11]
	v_readlane_b32 s92, v253, 0
	s_cbranch_execz .LBB0_1268
	v_readlane_b32 s98, v254, 54
	s_cmp_lg_u32 s98, 0
	s_cbranch_scc1 .Lmy_c2_normal
	v_readlane_b32 s98, v254, 63
	s_and_b32 s98, s98, 32
	s_cmp_eq_u32 s98, 0
	s_cbranch_scc1 .LBB0_1268
	s_movk_i32 s98, 4
	s_lshl_b32 s98, s98, 8
	s_add_i32 s98, s98, 0x40000
	s_add_u32 s98, s8, s98
	s_addc_u32 s99, s9, 0
	s_mov_b32 s100, 0

.Lmy_c2_done:
	buffer_inv sc1
	s_waitcnt vmcnt(0)
	s_branch .LBB0_1268
.Lmy_c2_normal:
	v_readlane_b32 s2, v254, 43
	s_waitcnt vmcnt(0) expcnt(0) lgkmcnt(0)
	s_nop 0
	v_mov_b32_e32 v0, s2
	ds_read_b32 v3, v0
	v_readlane_b32 s2, v254, 44
	s_waitcnt lgkmcnt(0)
	v_cmp_ne_u32_e32 vcc, 0, v3
	v_mov_b32_e32 v0, s2
	ds_read_b32 v2, v0
	s_cbranch_vccnz .LBB0_1232
	s_add_u32 s10, s8, 0x80200
	s_addc_u32 s11, s9, 0
	s_add_u32 s12, s8, 0x80400
	s_addc_u32 s13, s9, 0
	s_add_u32 s14, s8, 0x80500
	s_addc_u32 s15, s9, 0
	s_add_u32 s16, s8, 0x80600
	s_addc_u32 s17, s9, 0
	s_add_u32 s18, s8, 0x80700
	s_addc_u32 s19, s9, 0
	s_add_u32 s20, s8, 0x80800
	s_addc_u32 s21, s9, 0
	s_add_u32 s22, s8, 0x80900
	s_addc_u32 s23, s9, 0
	s_add_u32 s24, s8, 0x80a00
	s_addc_u32 s25, s9, 0
	s_add_u32 s26, s8, 0x80b00
	s_addc_u32 s27, s9, 0
	s_add_u32 s28, s8, 0x80c00
	s_addc_u32 s29, s9, 0
	s_add_u32 s30, s8, 0x80d00
	s_addc_u32 s31, s9, 0
	s_add_u32 s34, s8, 0x80e00
	s_addc_u32 s35, s9, 0
	s_add_u32 s36, s8, 0x80f00
	s_addc_u32 s37, s9, 0
	s_add_u32 s38, s8, 0x81000
	s_addc_u32 s39, s9, 0
	s_add_u32 s62, s8, 0x81100
	s_addc_u32 s63, s9, 0
	s_add_u32 s64, s8, 0x81200
	s_addc_u32 s65, s9, 0
	s_add_u32 s80, s8, 0x81300
	s_addc_u32 s81, s9, 0
	s_mov_b32 s2, 1
	s_branch .LBB0_1220

.LBB0_1268:
	s_or_b64 exec, exec, s[6:7]
	v_readlane_b32 s4, v253, 5
	v_readlane_b32 s5, v253, 6
	s_andn2_b64 vcc, exec, s[4:5]
	s_waitcnt lgkmcnt(0)
	s_barrier
	s_cbranch_vccnz .LBB0_156
	v_readlane_b32 s98, v254, 63
	s_and_b32 s98, s98, 32
	s_cmp_eq_u32 s98, 0
	s_cbranch_scc1 .LBB0_1272
	s_mov_b32 s99, 0
.Lmy_ln2_again:
	v_readlane_b32 s4, v253, 3
	v_readlane_b32 s5, v253, 4
	v_readlane_b32 s20, v254, 50
	v_readlane_b32 s22, v254, 52
	s_mov_b64 s[8:9], s[70:71]
	s_and_b64 vcc, exec, s[4:5]
	s_mov_b32 s18, 0x5200000
	s_mov_b32 s19, 0x9a00000
	v_readlane_b32 s21, v254, 51
	v_readlane_b32 s23, v254, 53
	v_mbcnt_lo_u32_b32 v0, -1, 0
	v_mbcnt_hi_u32_b32 v0, -1, v0
	s_cbranch_vccnz .LBB0_1272
	s_load_dwordx2 s[6:7], s[8:9], 0x88
	s_load_dwordx4 s[12:15], s[8:9], 0x30
	v_readlane_b32 s4, v253, 9
	v_lshlrev_b32_e32 v30, 2, v0
	v_and_b32_e32 v0, 64, v249
	v_readlane_b32 s5, v253, 10
	v_add_u32_e32 v0, 64, v0
	v_xor_b32_e32 v2, 1, v249
	s_lshl_b64 s[4:5], s[4:5], 2
	v_cmp_lt_i32_e32 vcc, v2, v0
	s_waitcnt lgkmcnt(0)
	s_add_u32 s2, s6, s4
	s_addc_u32 s16, s7, s5
	v_cndmask_b32_e32 v2, v249, v2, vcc
	v_lshlrev_b32_e32 v60, 2, v2
	v_xor_b32_e32 v2, 2, v249
	s_add_u32 s4, s2, 0x14d000
	v_cmp_lt_i32_e32 vcc, v2, v0
	s_addc_u32 s5, s16, 0
	s_lshl_b64 s[8:9], s[66:67], 2
	v_cndmask_b32_e32 v2, v249, v2, vcc
	s_add_u32 s10, s14, s8
	v_lshlrev_b32_e32 v61, 2, v2
	v_xor_b32_e32 v2, 4, v249
	s_addc_u32 s11, s15, s9
	v_cmp_lt_i32_e32 vcc, v2, v0
	s_add_u32 s8, s12, s8
	s_addc_u32 s9, s13, s9
	v_cndmask_b32_e32 v2, v249, v2, vcc
	v_lshlrev_b32_e32 v62, 2, v2
	v_xor_b32_e32 v2, 8, v249
	v_cmp_lt_i32_e32 vcc, v2, v0
	s_add_u32 s12, s2, 0x14e000
	s_addc_u32 s13, s16, 0
	v_cndmask_b32_e32 v2, v249, v2, vcc
	v_lshlrev_b32_e32 v63, 2, v2
	v_xor_b32_e32 v2, 16, v249
	s_add_u32 s14, s2, 0x14f000
	v_ashrrev_i32_e32 v31, 31, v30
	v_cmp_lt_i32_e32 vcc, v2, v0
	s_addc_u32 s15, s16, 0
	v_lshlrev_b64 v[34:35], 2, v[30:31]
	s_mov_b64 s[16:17], 0x400
	v_cndmask_b32_e32 v2, v249, v2, vcc
	v_lshl_add_u64 v[20:21], v[34:35], 0, s[16:17]
	s_mov_b64 s[16:17], 0x800
	v_lshlrev_b32_e32 v64, 2, v2
	v_xor_b32_e32 v2, 32, v249
	v_lshl_add_u64 v[24:25], v[34:35], 0, s[16:17]
	s_mov_b64 s[16:17], 0xc00
	v_cmp_lt_i32_e32 vcc, v2, v0
	v_lshl_add_u64 v[28:29], v[34:35], 0, s[16:17]
	v_lshl_add_u64 v[4:5], s[4:5], 0, v[20:21]
	v_cndmask_b32_e32 v0, v249, v2, vcc
	v_lshl_add_u64 v[2:3], s[4:5], 0, v[34:35]
	v_lshl_add_u64 v[6:7], s[4:5], 0, v[24:25]
	v_lshl_add_u64 v[8:9], s[4:5], 0, v[28:29]
	v_readlane_b32 s4, v254, 48
	v_lshlrev_b64 v[32:33], 1, v[30:31]
	v_readlane_b32 s5, v254, 49
	v_lshl_add_u64 v[10:11], s[8:9], 0, v[34:35]
	v_lshl_add_u64 v[12:13], s[10:11], 0, v[34:35]
	v_lshl_add_u64 v[30:31], s[4:5], 0, v[32:33]
	v_readlane_b32 s4, v254, 35
	v_readlane_b32 s5, v254, 36
	v_lshl_add_u64 v[14:15], s[14:15], 0, v[34:35]
	v_lshl_add_u64 v[16:17], s[12:13], 0, v[34:35]
	v_lshl_add_u64 v[32:33], s[4:5], 0, v[32:33]
	v_readlane_b32 s4, v254, 37
	v_readlane_b32 s5, v254, 38
	v_lshlrev_b32_e32 v65, 2, v0
	v_lshl_add_u64 v[18:19], s[14:15], 0, v[20:21]
	v_lshl_add_u64 v[34:35], s[4:5], 0, v[34:35]
	v_readlane_b32 s4, v254, 46
	v_lshl_add_u64 v[20:21], s[12:13], 0, v[20:21]
	v_lshl_add_u64 v[22:23], s[14:15], 0, v[24:25]
	v_lshl_add_u64 v[24:25], s[12:13], 0, v[24:25]
	v_lshl_add_u64 v[26:27], s[14:15], 0, v[28:29]
	v_lshl_add_u64 v[28:29], s[12:13], 0, v[28:29]
	s_mov_b32 s8, s4
	v_readlane_b32 s5, v254, 47
	s_cmp_eq_u32 s99, 0
	s_cbranch_scc1 .Lmy_ln2_nd
	s_add_i32 s8, s8, 0xffffff00
	s_mov_b32 s100, 0xfff80000
	s_mov_b32 s101, -1
	v_lshl_add_u64 v[30:31], v[30:31], 0, s[100:101]
	v_lshl_add_u64 v[32:33], v[32:33], 0, s[100:101]
	s_mov_b32 s100, 0xfff00000
	v_lshl_add_u64 v[34:35], v[34:35], 0, s[100:101]
.Lmy_ln2_nd:
.LBB0_1271:
	v_lshl_add_u64 v[48:49], s[6:7], 0, v[34:35]
	v_add_co_u32_e32 v76, vcc, 0x12a00000, v48
	s_nop 1
	v_addc_co_u32_e32 v77, vcc, 0, v49, vcc
	v_add_co_u32_e32 v78, vcc, 0x13200000, v48
	s_nop 1
	v_addc_co_u32_e32 v79, vcc, 0, v49, vcc
	v_add_co_u32_e32 v80, vcc, 0x13a00000, v48
	s_nop 1
	v_addc_co_u32_e32 v81, vcc, 0, v49, vcc
	v_add_co_u32_e32 v82, vcc, 0x14200000, v48
	s_nop 1
	v_addc_co_u32_e32 v83, vcc, 0, v49, vcc
	v_lshl_add_u64 v[84:85], s[6:7], 0, v[32:33]
	v_add_co_u32_e32 v84, vcc, 0x7200000, v84
	s_nop 1
	v_addc_co_u32_e32 v85, vcc, 0, v85, vcc
	global_load_dwordx4 v[86:89], v[76:77], off
	global_load_dwordx4 v[90:93], v[78:79], off
	global_load_dwordx4 v[94:97], v[80:81], off
	global_load_dwordx4 v[98:101], v[82:83], off
	global_load_dwordx2 v[102:103], v[84:85], off
	global_load_dwordx4 v[104:107], v[2:3], off
	global_load_dwordx4 v[108:111], v[76:77], off offset:1024
	global_load_dwordx4 v[112:115], v[78:79], off offset:1024
	global_load_dwordx4 v[116:119], v[80:81], off offset:1024
	global_load_dwordx4 v[120:123], v[82:83], off offset:1024
	global_load_dwordx2 v[124:125], v[84:85], off offset:512
	global_load_dwordx4 v[126:129], v[4:5], off
	global_load_dwordx4 v[130:133], v[76:77], off offset:2048
	global_load_dwordx4 v[134:137], v[78:79], off offset:2048
	global_load_dwordx4 v[138:141], v[80:81], off offset:2048
	global_load_dwordx4 v[142:145], v[82:83], off offset:2048
	global_load_dwordx2 v[146:147], v[84:85], off offset:1024
	global_load_dwordx4 v[148:151], v[6:7], off
	global_load_dwordx4 v[152:155], v[76:77], off offset:3072
	global_load_dwordx4 v[156:159], v[78:79], off offset:3072
	global_load_dwordx4 v[160:163], v[80:81], off offset:3072
	global_load_dwordx4 v[164:167], v[82:83], off offset:3072
	global_load_dwordx2 v[168:169], v[84:85], off offset:1536
	global_load_dwordx4 v[170:173], v[8:9], off
	s_waitcnt vmcnt(0)
	s_add_i32 s8, s8, s38
	s_nop 0
	s_nop 0
	v_lshl_add_u64 v[34:35], v[34:35], 0, s[22:23]
	s_nop 0
	s_cmpk_lt_i32 s8, 0x4800
	s_nop 0
	v_pk_add_f32 v[50:51], v[88:89], v[92:93]
	v_pk_add_f32 v[56:57], v[86:87], v[90:91]
	v_pk_add_f32 v[36:37], v[94:95], v[98:99]
	v_pk_add_f32 v[38:39], v[96:97], v[100:101]
	v_pk_add_f32 v[42:43], v[56:57], v[36:37]
	v_pk_add_f32 v[40:41], v[50:51], v[38:39]
	s_nop 0
	v_lshl_add_u64 v[32:33], v[32:33], 0, s[20:21]
	v_cvt_f32_f16_e32 v48, v102
	v_cvt_f32_f16_sdwa v49, v102 dst_sel:DWORD dst_unused:UNUSED_PAD src0_sel:WORD_1
	v_cvt_f32_f16_e32 v50, v103
	v_cvt_f32_f16_sdwa v51, v103 dst_sel:DWORD dst_unused:UNUSED_PAD src0_sel:WORD_1
	v_pk_mul_f32 v[38:39], v[40:41], v[106:107]
	v_pk_mul_f32 v[36:37], v[42:43], v[104:105]
	v_pk_fma_f32 v[50:51], v[50:51], s[90:91], v[38:39] op_sel_hi:[1, 0, 1]
	v_pk_fma_f32 v[48:49], v[48:49], s[90:91], v[36:37] op_sel_hi:[1, 0, 1]
	v_mov_b32_e32 v39, v51
	v_pk_mov_b32 v[36:37], v[48:49], v[50:51] op_sel:[1, 0]
	v_mov_b32_e32 v38, v48
	v_pk_add_f32 v[36:37], v[36:37], v[38:39]
	s_nop 0
	v_add_f32_e32 v0, v36, v37
	v_add_f32_e32 v56, 0, v0
	v_pk_add_f32 v[66:67], v[110:111], v[114:115]
	v_pk_add_f32 v[68:69], v[108:109], v[112:113]
	v_pk_add_f32 v[36:37], v[116:117], v[120:121]
	v_pk_add_f32 v[38:39], v[118:119], v[122:123]
	v_pk_add_f32 v[42:43], v[68:69], v[36:37]
	v_pk_add_f32 v[40:41], v[66:67], v[38:39]
	v_cvt_f32_f16_e32 v66, v124
	v_cvt_f32_f16_sdwa v67, v124 dst_sel:DWORD dst_unused:UNUSED_PAD src0_sel:WORD_1
	v_cvt_f32_f16_e32 v68, v125
	v_cvt_f32_f16_sdwa v69, v125 dst_sel:DWORD dst_unused:UNUSED_PAD src0_sel:WORD_1
	v_pk_mul_f32 v[38:39], v[40:41], v[128:129]
	v_pk_mul_f32 v[40:41], v[42:43], v[126:127]
	v_pk_fma_f32 v[36:37], v[68:69], s[90:91], v[38:39] op_sel_hi:[1, 0, 1]
	v_pk_fma_f32 v[38:39], v[66:67], s[90:91], v[40:41] op_sel_hi:[1, 0, 1]
	v_mov_b32_e32 v43, v37
	v_pk_mov_b32 v[40:41], v[38:39], v[36:37] op_sel:[1, 0]
	v_mov_b32_e32 v42, v38
	v_pk_add_f32 v[40:41], v[40:41], v[42:43]
	s_nop 0
	v_pk_add_f32 v[70:71], v[40:41], v[40:41] op_sel:[0, 1] op_sel_hi:[1, 0]
	v_pk_add_f32 v[72:73], v[132:133], v[136:137]
	v_pk_add_f32 v[74:75], v[130:131], v[134:135]
	v_pk_add_f32 v[40:41], v[138:139], v[142:143]
	v_pk_add_f32 v[42:43], v[140:141], v[144:145]
	v_pk_add_f32 v[68:69], v[74:75], v[40:41]
	v_pk_add_f32 v[66:67], v[72:73], v[42:43]
	v_cvt_f32_f16_e32 v72, v146
	v_cvt_f32_f16_sdwa v73, v146 dst_sel:DWORD dst_unused:UNUSED_PAD src0_sel:WORD_1
	v_cvt_f32_f16_e32 v74, v147
	v_cvt_f32_f16_sdwa v75, v147 dst_sel:DWORD dst_unused:UNUSED_PAD src0_sel:WORD_1
	v_pk_mul_f32 v[42:43], v[66:67], v[150:151]
	v_pk_mul_f32 v[66:67], v[68:69], v[148:149]
	v_pk_fma_f32 v[40:41], v[74:75], s[90:91], v[42:43] op_sel_hi:[1, 0, 1]
	v_pk_fma_f32 v[42:43], v[72:73], s[90:91], v[66:67] op_sel_hi:[1, 0, 1]
	s_nop 0
	v_add_f32_e32 v72, v42, v43
	v_add_f32_e32 v74, v40, v41
	v_pk_add_f32 v[68:69], v[154:155], v[158:159]
	v_pk_add_f32 v[66:67], v[152:153], v[156:157]
	s_nop 0
	v_pk_add_f32 v[44:45], v[160:161], v[164:165]
	v_pk_add_f32 v[46:47], v[162:163], v[166:167]
	v_pk_add_f32 v[54:55], v[66:67], v[44:45]
	v_pk_add_f32 v[52:53], v[68:69], v[46:47]
	v_cvt_f32_f16_e32 v58, v168
	v_cvt_f32_f16_sdwa v59, v168 dst_sel:DWORD dst_unused:UNUSED_PAD src0_sel:WORD_1
	v_cvt_f32_f16_e32 v66, v169
	v_cvt_f32_f16_sdwa v67, v169 dst_sel:DWORD dst_unused:UNUSED_PAD src0_sel:WORD_1
	v_pk_mul_f32 v[46:47], v[52:53], v[172:173]
	v_pk_mul_f32 v[52:53], v[54:55], v[170:171]
	v_pk_fma_f32 v[44:45], v[66:67], s[90:91], v[46:47] op_sel_hi:[1, 0, 1]
	v_pk_fma_f32 v[46:47], v[58:59], s[90:91], v[52:53] op_sel_hi:[1, 0, 1]
	v_mov_b32_e32 v73, v44
	v_mov_b32_e32 v57, v46
	v_mov_b32_e32 v71, v47
	v_mov_b32_e32 v75, v45
	v_pk_add_f32 v[52:53], v[56:57], v[70:71]
	v_pk_add_f32 v[54:55], v[72:73], v[74:75]
	s_nop 0
	v_pk_add_f32 v[52:53], v[52:53], v[54:55]
	s_nop 0
	v_add_f32_e32 v0, v52, v53
	ds_bpermute_b32 v52, v60, v0
	s_waitcnt lgkmcnt(0)
	v_add_f32_e32 v0, v0, v52
	ds_bpermute_b32 v52, v61, v0
	s_waitcnt lgkmcnt(0)
	v_add_f32_e32 v0, v0, v52
	ds_bpermute_b32 v52, v62, v0
	s_waitcnt lgkmcnt(0)
	v_add_f32_e32 v0, v0, v52
	ds_bpermute_b32 v52, v63, v0
	s_waitcnt lgkmcnt(0)
	v_add_f32_e32 v0, v0, v52
	ds_bpermute_b32 v52, v64, v0
	s_waitcnt lgkmcnt(0)
	v_add_f32_e32 v0, v0, v52
	ds_bpermute_b32 v52, v65, v0
	s_waitcnt lgkmcnt(0)
	v_add_f32_e32 v66, v0, v52
	v_fmamk_f32 v49, v66, 0xba800000, v49
	v_fmac_f32_e32 v48, 0xba800000, v66
	v_fmamk_f32 v51, v66, 0xba800000, v51
	v_fmac_f32_e32 v50, 0xba800000, v66
	v_pk_mul_f32 v[52:53], v[50:51], v[50:51]
	v_pk_mul_f32 v[54:55], v[48:49], v[48:49]
	v_fmamk_f32 v39, v66, 0xba800000, v39
	v_pk_mov_b32 v[56:57], v[54:55], v[52:53] op_sel:[1,0]
	v_mov_b32_e32 v55, v53
	v_fmac_f32_e32 v38, 0xba800000, v66
	v_fmamk_f32 v37, v66, 0xba800000, v37
	v_fmac_f32_e32 v36, 0xba800000, v66
	v_pk_add_f32 v[52:53], v[56:57], v[54:55]
	v_pk_mul_f32 v[54:55], v[36:37], v[36:37]
	v_pk_mul_f32 v[56:57], v[38:39], v[38:39]
	v_fmac_f32_e32 v42, 0xba800000, v66
	v_pk_mov_b32 v[58:59], v[56:57], v[54:55] op_sel:[1,0]
	v_mov_b32_e32 v57, v55
	v_fmamk_f32 v43, v66, 0xba800000, v43
	v_fmac_f32_e32 v40, 0xba800000, v66
	v_mul_f32_e32 v0, v42, v42
	v_pk_add_f32 v[54:55], v[58:59], v[56:57]
	v_fmamk_f32 v41, v66, 0xba800000, v41
	v_pk_fma_f32 v[56:57], v[42:43], v[42:43], v[0:1] op_sel_hi:[1,1,0]
	v_mul_f32_e32 v0, v40, v40
	v_pk_add_f32 v[52:53], v[52:53], v[52:53] op_sel_hi:[0,1]
	v_pk_add_f32 v[54:55], v[54:55], v[54:55] op_sel_hi:[0,1]
	v_pk_fma_f32 v[58:59], v[40:41], v[40:41], v[0:1] op_sel_hi:[1,1,0]
	v_fmamk_f32 v45, v66, 0xba800000, v45
	v_fmac_f32_e32 v44, 0xba800000, v66
	v_fmamk_f32 v47, v66, 0xba800000, v47
	v_fmac_f32_e32 v46, 0xba800000, v66
	v_mul_f32_e32 v56, v46, v46
	v_mul_f32_e32 v58, v47, v47
	v_mul_f32_e32 v52, v44, v44
	v_mul_f32_e32 v54, v45, v45
	v_pk_add_f32 v[56:57], v[56:57], v[58:59]
	v_pk_add_f32 v[52:53], v[52:53], v[54:55]
	s_nop 0
	v_pk_add_f32 v[52:53], v[56:57], v[52:53]
	s_nop 0
	v_add_f32_e32 v0, v52, v53
	ds_bpermute_b32 v52, v60, v0
	s_waitcnt lgkmcnt(0)
	v_add_f32_e32 v0, v0, v52
	ds_bpermute_b32 v52, v61, v0
	s_waitcnt lgkmcnt(0)
	v_add_f32_e32 v0, v0, v52
	ds_bpermute_b32 v52, v62, v0
	s_waitcnt lgkmcnt(0)
	v_add_f32_e32 v0, v0, v52
	ds_bpermute_b32 v52, v63, v0
	s_waitcnt lgkmcnt(0)
	v_add_f32_e32 v0, v0, v52
	ds_bpermute_b32 v52, v64, v0
	s_waitcnt lgkmcnt(0)
	v_add_f32_e32 v0, v0, v52
	ds_bpermute_b32 v52, v65, v0
	s_waitcnt lgkmcnt(0)
	v_add_f32_e32 v0, v0, v52
	global_load_dwordx4 v[76:79], v[10:11], off
	global_load_dwordx4 v[80:83], v[12:13], off
	global_load_dwordx4 v[84:87], v[14:15], off
	global_load_dwordx4 v[88:91], v[16:17], off
	global_load_dwordx4 v[92:95], v[10:11], off offset:1024
	global_load_dwordx4 v[96:99], v[12:13], off offset:1024
	global_load_dwordx4 v[100:103], v[18:19], off
	global_load_dwordx4 v[104:107], v[20:21], off
	global_load_dwordx4 v[108:111], v[10:11], off offset:2048
	global_load_dwordx4 v[112:115], v[12:13], off offset:2048
	global_load_dwordx4 v[116:119], v[22:23], off
	global_load_dwordx4 v[120:123], v[24:25], off
	global_load_dwordx4 v[124:127], v[10:11], off offset:3072
	global_load_dwordx4 v[128:131], v[12:13], off offset:3072
	global_load_dwordx4 v[132:135], v[26:27], off
	global_load_dwordx4 v[136:139], v[28:29], off
	s_waitcnt vmcnt(0)
	v_fmamk_f32 v0, v0, 0x3a800000, v247
	v_cmp_gt_f32_e32 vcc, s96, v0
	v_mul_f32_e32 v52, 0x4f800000, v0
	s_nop 0
	v_cndmask_b32_e32 v0, v0, v52, vcc
	v_sqrt_f32_e32 v52, v0
	s_nop 0
	v_add_u32_e32 v53, -1, v52
	v_fma_f32 v54, -v53, v52, v0
	v_cmp_ge_f32_e64 s[4:5], 0, v54
	v_add_u32_e32 v54, 1, v52
	s_nop 0
	v_cndmask_b32_e64 v53, v52, v53, s[4:5]
	v_fma_f32 v52, -v54, v52, v0
	v_cmp_lt_f32_e64 s[4:5], 0, v52
	s_nop 1
	v_cndmask_b32_e64 v52, v53, v54, s[4:5]
	v_mul_f32_e32 v53, 0x37800000, v52
	v_cndmask_b32_e32 v52, v52, v53, vcc
	v_cmp_class_f32_e32 vcc, v0, v248
	s_nop 1
	v_cndmask_b32_e32 v0, v52, v0, vcc
	v_div_scale_f32 v52, s[4:5], v0, v0, 1.0
	v_rcp_f32_e32 v53, v52
	s_nop 0
	v_fma_f32 v54, -v52, v53, 1.0
	v_fmac_f32_e32 v53, v54, v53
	v_div_scale_f32 v54, vcc, 1.0, v0, 1.0
	v_mul_f32_e32 v55, v54, v53
	v_fma_f32 v56, -v52, v55, v54
	v_fmac_f32_e32 v55, v56, v53
	v_fma_f32 v52, -v52, v55, v54
	v_div_fmas_f32 v52, v52, v53, v55
	v_div_fixup_f32 v0, v52, v0, 1.0
	v_pk_mul_f32 v[50:51], v[50:51], v[0:1] op_sel_hi:[1, 0]
	v_pk_mul_f32 v[48:49], v[48:49], v[0:1] op_sel_hi:[1, 0]
	v_pk_mul_f32 v[46:47], v[46:47], v[0:1] op_sel_hi:[1, 0]
	v_pk_mul_f32 v[44:45], v[44:45], v[0:1] op_sel_hi:[1, 0]
	v_pk_fma_f32 v[54:55], v[78:79], v[50:51], v[82:83]
	v_lshl_add_u64 v[50:51], s[6:7], 0, v[30:31]
	v_pk_fma_f32 v[52:53], v[76:77], v[48:49], v[80:81]
	v_add_co_u32_e32 v48, vcc, s18, v50
	v_cvt_pk_f16_f32 v57, v54, v55
	v_cvt_pk_f16_f32 v56, v52, v53
	v_addc_co_u32_e32 v49, vcc, 0, v51, vcc
	global_store_dwordx2 v[48:49], v[56:57], off
	v_lshl_add_u64 v[30:31], v[30:31], 0, s[20:21]
	v_pk_add_f32 v[66:67], v[86:87], 1.0 op_sel_hi:[1, 0]
	v_pk_add_f32 v[68:69], v[84:85], 1.0 op_sel_hi:[1, 0]
	v_pk_fma_f32 v[54:55], v[66:67], v[54:55], v[90:91]
	v_pk_fma_f32 v[52:53], v[68:69], v[52:53], v[88:89]
	v_pk_mul_f32 v[56:57], v[38:39], v[0:1] op_sel_hi:[1, 0]
	v_cvt_pk_bf16_f32 v52, v52, v53
	v_cvt_pk_bf16_f32 v53, v54, v55
	v_add_co_u32_e32 v54, vcc, s19, v50
	v_pk_mul_f32 v[58:59], v[36:37], v[0:1] op_sel_hi:[1, 0]
	s_nop 0
	v_addc_co_u32_e32 v55, vcc, 0, v51, vcc
	global_store_dwordx2 v[54:55], v[52:53], off
	s_nop 0
	v_pk_fma_f32 v[52:53], v[94:95], v[58:59], v[98:99]
	v_pk_fma_f32 v[50:51], v[92:93], v[56:57], v[96:97]
	v_cvt_pk_f16_f32 v37, v52, v53
	v_cvt_pk_f16_f32 v36, v50, v51
	global_store_dwordx2 v[48:49], v[36:37], off offset:512
	v_pk_add_f32 v[56:57], v[102:103], 1.0 op_sel_hi:[1, 0]
	v_pk_add_f32 v[58:59], v[100:101], 1.0 op_sel_hi:[1, 0]
	v_pk_fma_f32 v[36:37], v[58:59], v[50:51], v[104:105]
	v_pk_fma_f32 v[38:39], v[56:57], v[52:53], v[106:107]
	v_cvt_pk_bf16_f32 v36, v36, v37
	v_pk_mul_f32 v[50:51], v[42:43], v[0:1] op_sel_hi:[1, 0]
	v_cvt_pk_bf16_f32 v37, v38, v39
	global_store_dwordx2 v[54:55], v[36:37], off offset:512
	v_pk_mul_f32 v[52:53], v[40:41], v[0:1] op_sel_hi:[1, 0]
	v_pk_fma_f32 v[42:43], v[110:111], v[52:53], v[114:115]
	v_pk_fma_f32 v[40:41], v[108:109], v[50:51], v[112:113]
	v_cvt_pk_f16_f32 v37, v42, v43
	v_cvt_pk_f16_f32 v36, v40, v41
	global_store_dwordx2 v[48:49], v[36:37], off offset:1024
	v_pk_add_f32 v[50:51], v[118:119], 1.0 op_sel_hi:[1, 0]
	v_pk_add_f32 v[52:53], v[116:117], 1.0 op_sel_hi:[1, 0]
	v_pk_fma_f32 v[36:37], v[52:53], v[40:41], v[120:121]
	v_pk_fma_f32 v[38:39], v[50:51], v[42:43], v[122:123]
	v_cvt_pk_bf16_f32 v36, v36, v37
	s_nop 0
	v_cvt_pk_bf16_f32 v37, v38, v39
	global_store_dwordx2 v[54:55], v[36:37], off offset:1024
	s_nop 0
	v_pk_fma_f32 v[42:43], v[44:45], v[126:127], v[130:131]
	v_pk_fma_f32 v[40:41], v[46:47], v[124:125], v[128:129]
	v_cvt_pk_f16_f32 v37, v42, v43
	v_cvt_pk_f16_f32 v36, v40, v41
	global_store_dwordx2 v[48:49], v[36:37], off offset:1536
	v_pk_add_f32 v[44:45], v[134:135], 1.0 op_sel_hi:[1, 0]
	v_pk_add_f32 v[46:47], v[132:133], 1.0 op_sel_hi:[1, 0]
	v_pk_fma_f32 v[36:37], v[40:41], v[46:47], v[136:137]
	v_pk_fma_f32 v[38:39], v[42:43], v[44:45], v[138:139]
	v_cvt_pk_bf16_f32 v36, v36, v37
	s_nop 0
	v_cvt_pk_bf16_f32 v37, v38, v39
	global_store_dwordx2 v[54:55], v[36:37], off offset:1536
	s_cbranch_scc1 .LBB0_1271
	s_xor_b32 s99, s99, 1
	s_cmp_lg_u32 s99, 0
	s_cbranch_scc1 .Lmy_ln2_again
